# same schedule as previous, plus two wait states between v_permlane32_swap and the v_max that reads its result (hazard safety)
# speedup vs baseline: 1.0033x; 1.0033x over previous
; DI void softmax_pv(f32x16 (&sa)[2], f32x16 (&O)[4], float& m, float& l, const char* sV, int lr, int lh, bool first) {
;   float t0 = fmaxf(fmaxf(sa[0][0], sa[0][1]), sa[0][2]);
;   float t1 = fmaxf(fmaxf(sa[1][0], sa[1][1]), sa[1][2]);
; #pragma unroll
;   for (int i = 3; i < 15; i += 2) {
;     t0 = fmaxf(fmaxf(t0, sa[0][i]), sa[0][i + 1]);
;     t1 = fmaxf(fmaxf(t1, sa[1][i]), sa[1][i + 1]);
;   }
;   float tmax = fmaxf(fmaxf(t0, t1), fmaxf(sa[0][15], sa[1][15]));
;   tmax = fmaxf(tmax, __shfl_xor(tmax, 32, 64));
;   if (first || __any(tmax > SM_THR)) {
;     asm volatile("; rescale" ::: "memory");
;     const float delta = first ? tmax : fmaxf(tmax, 0.f);
;     const float alpha = __builtin_amdgcn_exp2f(-delta);
;     m += delta;
;     l *= alpha;
; #pragma unroll
;     for (int d = 0; d < 4; ++d)
; #pragma unroll
;       for (int i = 0; i < 16; ++i) O[d][i] *= alpha;
; #pragma unroll
;     for (int i = 0; i < 16; ++i) { sa[0][i] -= delta; sa[1][i] -= delta; }
;   }
.LBB0_130:
	v_max3_f32 v172, v80, v81, v82
	s_nop 1
	v_max3_f32 v173, v64, v65, v66
	v_max3_f32 v172, v172, v83, v84
	v_max3_f32 v173, v173, v67, v68
	v_max3_f32 v172, v172, v85, v86
	v_max3_f32 v173, v173, v69, v70
	v_max3_f32 v172, v172, v87, v88
	v_max3_f32 v173, v173, v71, v72
	v_max3_f32 v172, v172, v89, v90
	v_max3_f32 v173, v173, v73, v74
	v_max3_f32 v172, v172, v91, v92
	v_max3_f32 v173, v173, v75, v76
	v_max_f32_e32 v174, v79, v79
	v_max_f32_e32 v175, v95, v95
	v_max3_f32 v172, v172, v93, v94
	v_max3_f32 v173, v173, v77, v78
	v_max_f32_e32 v174, v175, v174
	v_max3_f32 v172, v172, v173, v174
	v_mov_b32_e32 v173, v172
	s_mov_b32 s10, 0x41000000
	s_nop 0
	v_permlane32_swap_b32_e32 v173, v172
	s_nop 1
	v_max_f32_e32 v172, v172, v173
	v_cmp_lt_f32_e32 vcc, s10, v172
	s_cbranch_vccz .LBB0_132
	v_max_f32_e32 v172, v172, v172
	v_max_f32_e32 v172, 0, v172
	v_exp_f32_e64 v174, -v172
	v_add_f32_e32 v166, v166, v172
	v_pk_add_f32 v[80:81], v[80:81], v[172:173] op_sel_hi:[1,0] neg_lo:[0,1] neg_hi:[0,1]
	v_mul_f32_e32 v163, v163, v174
	v_pk_mul_f32 v[62:63], v[62:63], v[174:175] op_sel_hi:[1,0]
	v_pk_mul_f32 v[60:61], v[60:61], v[174:175] op_sel_hi:[1,0]
	v_pk_mul_f32 v[58:59], v[58:59], v[174:175] op_sel_hi:[1,0]
	v_pk_mul_f32 v[56:57], v[56:57], v[174:175] op_sel_hi:[1,0]
	v_pk_mul_f32 v[54:55], v[54:55], v[174:175] op_sel_hi:[1,0]
	v_pk_mul_f32 v[52:53], v[52:53], v[174:175] op_sel_hi:[1,0]
	v_pk_mul_f32 v[50:51], v[50:51], v[174:175] op_sel_hi:[1,0]
	v_pk_mul_f32 v[48:49], v[48:49], v[174:175] op_sel_hi:[1,0]
	v_pk_mul_f32 v[46:47], v[46:47], v[174:175] op_sel_hi:[1,0]
	v_pk_mul_f32 v[44:45], v[44:45], v[174:175] op_sel_hi:[1,0]
	v_pk_mul_f32 v[42:43], v[42:43], v[174:175] op_sel_hi:[1,0]
	v_pk_mul_f32 v[40:41], v[40:41], v[174:175] op_sel_hi:[1,0]
	v_pk_mul_f32 v[38:39], v[38:39], v[174:175] op_sel_hi:[1,0]
	v_pk_mul_f32 v[36:37], v[36:37], v[174:175] op_sel_hi:[1,0]
	v_pk_mul_f32 v[34:35], v[34:35], v[174:175] op_sel_hi:[1,0]
	v_pk_mul_f32 v[32:33], v[32:33], v[174:175] op_sel_hi:[1,0]
	v_pk_mul_f32 v[30:31], v[30:31], v[174:175] op_sel_hi:[1,0]
	v_pk_mul_f32 v[28:29], v[28:29], v[174:175] op_sel_hi:[1,0]
	v_pk_mul_f32 v[26:27], v[26:27], v[174:175] op_sel_hi:[1,0]
	v_pk_mul_f32 v[24:25], v[24:25], v[174:175] op_sel_hi:[1,0]
	v_pk_mul_f32 v[22:23], v[22:23], v[174:175] op_sel_hi:[1,0]
	v_pk_mul_f32 v[20:21], v[20:21], v[174:175] op_sel_hi:[1,0]
	v_pk_mul_f32 v[18:19], v[18:19], v[174:175] op_sel_hi:[1,0]
	v_pk_mul_f32 v[16:17], v[16:17], v[174:175] op_sel_hi:[1,0]
	v_pk_mul_f32 v[14:15], v[14:15], v[174:175] op_sel_hi:[1,0]
	v_pk_mul_f32 v[12:13], v[12:13], v[174:175] op_sel_hi:[1,0]
	v_pk_mul_f32 v[10:11], v[10:11], v[174:175] op_sel_hi:[1,0]
	v_pk_mul_f32 v[8:9], v[8:9], v[174:175] op_sel_hi:[1,0]
	v_pk_mul_f32 v[6:7], v[6:7], v[174:175] op_sel_hi:[1,0]
	v_pk_mul_f32 v[4:5], v[4:5], v[174:175] op_sel_hi:[1,0]
	v_pk_mul_f32 v[2:3], v[2:3], v[174:175] op_sel_hi:[1,0]
	v_pk_mul_f32 v[0:1], v[0:1], v[174:175] op_sel_hi:[1,0]
	v_pk_add_f32 v[64:65], v[64:65], v[172:173] op_sel_hi:[1,0] neg_lo:[0,1] neg_hi:[0,1]
	v_pk_add_f32 v[82:83], v[82:83], v[172:173] op_sel_hi:[1,0] neg_lo:[0,1] neg_hi:[0,1]
	v_pk_add_f32 v[66:67], v[66:67], v[172:173] op_sel_hi:[1,0] neg_lo:[0,1] neg_hi:[0,1]
	v_pk_add_f32 v[84:85], v[84:85], v[172:173] op_sel_hi:[1,0] neg_lo:[0,1] neg_hi:[0,1]
	v_pk_add_f32 v[68:69], v[68:69], v[172:173] op_sel_hi:[1,0] neg_lo:[0,1] neg_hi:[0,1]
	v_pk_add_f32 v[86:87], v[86:87], v[172:173] op_sel_hi:[1,0] neg_lo:[0,1] neg_hi:[0,1]
	v_pk_add_f32 v[70:71], v[70:71], v[172:173] op_sel_hi:[1,0] neg_lo:[0,1] neg_hi:[0,1]
	v_pk_add_f32 v[88:89], v[88:89], v[172:173] op_sel_hi:[1,0] neg_lo:[0,1] neg_hi:[0,1]
	v_pk_add_f32 v[72:73], v[72:73], v[172:173] op_sel_hi:[1,0] neg_lo:[0,1] neg_hi:[0,1]
	v_pk_add_f32 v[90:91], v[90:91], v[172:173] op_sel_hi:[1,0] neg_lo:[0,1] neg_hi:[0,1]
	v_pk_add_f32 v[74:75], v[74:75], v[172:173] op_sel_hi:[1,0] neg_lo:[0,1] neg_hi:[0,1]
	v_pk_add_f32 v[92:93], v[92:93], v[172:173] op_sel_hi:[1,0] neg_lo:[0,1] neg_hi:[0,1]
	v_pk_add_f32 v[76:77], v[76:77], v[172:173] op_sel_hi:[1,0] neg_lo:[0,1] neg_hi:[0,1]
	v_pk_add_f32 v[94:95], v[94:95], v[172:173] op_sel_hi:[1,0] neg_lo:[0,1] neg_hi:[0,1]
	v_pk_add_f32 v[78:79], v[78:79], v[172:173] op_sel_hi:[1,0] neg_lo:[0,1] neg_hi:[0,1]

; DI void softmax_pv(f32x16 (&sa)[2], f32x16 (&O)[4], float& m, float& l, const char* sV, int lr, int lh, bool first) {
;   float t0 = fmaxf(fmaxf(sa[0][0], sa[0][1]), sa[0][2]);
;   float t1 = fmaxf(fmaxf(sa[1][0], sa[1][1]), sa[1][2]);
; #pragma unroll
;   for (int i = 3; i < 15; i += 2) {
;     t0 = fmaxf(fmaxf(t0, sa[0][i]), sa[0][i + 1]);
;     t1 = fmaxf(fmaxf(t1, sa[1][i]), sa[1][i + 1]);
;   }
;   float tmax = fmaxf(fmaxf(t0, t1), fmaxf(sa[0][15], sa[1][15]));
;   tmax = fmaxf(tmax, __shfl_xor(tmax, 32, 64));
;   if (first || __any(tmax > SM_THR)) {
;     asm volatile("; rescale" ::: "memory");
;     const float delta = first ? tmax : fmaxf(tmax, 0.f);
;     const float alpha = __builtin_amdgcn_exp2f(-delta);
;     m += delta;
;     l *= alpha;
; #pragma unroll
;     for (int d = 0; d < 4; ++d)
; #pragma unroll
;       for (int i = 0; i < 16; ++i) O[d][i] *= alpha;
; #pragma unroll
;     for (int i = 0; i < 16; ++i) { sa[0][i] -= delta; sa[1][i] -= delta; }
;   }
.LBB0_158:
	s_nop 3
	v_max3_f32 v184, v80, v81, v82
	s_nop 0
	v_max3_f32 v202, v64, v65, v66
	v_max3_f32 v184, v184, v83, v84
	v_max3_f32 v202, v202, v67, v68
	v_max3_f32 v184, v184, v85, v86
	v_max3_f32 v202, v202, v69, v70
	v_max3_f32 v184, v184, v87, v88
	v_max3_f32 v202, v202, v71, v72
	v_max3_f32 v184, v184, v89, v90
	v_max3_f32 v202, v202, v73, v74
	v_max3_f32 v184, v184, v91, v92
	v_max3_f32 v202, v202, v75, v76
	v_max_f32_e32 v203, v79, v79
	v_max_f32_e32 v204, v95, v95
	v_max3_f32 v184, v184, v93, v94
	v_max3_f32 v202, v202, v77, v78
	v_max_f32_e32 v203, v204, v203
	v_max3_f32 v184, v184, v202, v203
	v_mov_b32_e32 v202, v184
	s_nop 1
	v_permlane32_swap_b32_e32 v202, v184
	s_nop 1
	v_max_f32_e32 v184, v184, v202
	v_cmp_lt_f32_e32 vcc, s93, v184
	s_cbranch_vccz .LBB0_160
	v_max_f32_e32 v184, v184, v184
	v_max_f32_e32 v184, 0, v184
	v_exp_f32_e64 v202, -v184
	v_add_f32_e32 v226, v226, v184
	v_pk_add_f32 v[80:81], v[80:81], v[184:185] op_sel_hi:[1,0] neg_lo:[0,1] neg_hi:[0,1]
	v_mul_f32_e32 v222, v222, v202
	v_pk_mul_f32 v[62:63], v[62:63], v[202:203] op_sel_hi:[1,0]
	v_pk_mul_f32 v[60:61], v[60:61], v[202:203] op_sel_hi:[1,0]
	v_pk_mul_f32 v[58:59], v[58:59], v[202:203] op_sel_hi:[1,0]
	v_pk_mul_f32 v[56:57], v[56:57], v[202:203] op_sel_hi:[1,0]
	v_pk_mul_f32 v[54:55], v[54:55], v[202:203] op_sel_hi:[1,0]
	v_pk_mul_f32 v[52:53], v[52:53], v[202:203] op_sel_hi:[1,0]
	v_pk_mul_f32 v[50:51], v[50:51], v[202:203] op_sel_hi:[1,0]
	v_pk_mul_f32 v[48:49], v[48:49], v[202:203] op_sel_hi:[1,0]
	v_pk_mul_f32 v[46:47], v[46:47], v[202:203] op_sel_hi:[1,0]
	v_pk_mul_f32 v[44:45], v[44:45], v[202:203] op_sel_hi:[1,0]
	v_pk_mul_f32 v[42:43], v[42:43], v[202:203] op_sel_hi:[1,0]
	v_pk_mul_f32 v[40:41], v[40:41], v[202:203] op_sel_hi:[1,0]
	v_pk_mul_f32 v[38:39], v[38:39], v[202:203] op_sel_hi:[1,0]
	v_pk_mul_f32 v[36:37], v[36:37], v[202:203] op_sel_hi:[1,0]
	v_pk_mul_f32 v[34:35], v[34:35], v[202:203] op_sel_hi:[1,0]
	v_pk_mul_f32 v[32:33], v[32:33], v[202:203] op_sel_hi:[1,0]
	v_pk_mul_f32 v[30:31], v[30:31], v[202:203] op_sel_hi:[1,0]
	v_pk_mul_f32 v[28:29], v[28:29], v[202:203] op_sel_hi:[1,0]
	v_pk_mul_f32 v[26:27], v[26:27], v[202:203] op_sel_hi:[1,0]
	v_pk_mul_f32 v[24:25], v[24:25], v[202:203] op_sel_hi:[1,0]
	v_pk_mul_f32 v[22:23], v[22:23], v[202:203] op_sel_hi:[1,0]
	v_pk_mul_f32 v[20:21], v[20:21], v[202:203] op_sel_hi:[1,0]
	v_pk_mul_f32 v[18:19], v[18:19], v[202:203] op_sel_hi:[1,0]
	v_pk_mul_f32 v[16:17], v[16:17], v[202:203] op_sel_hi:[1,0]
	v_pk_mul_f32 v[14:15], v[14:15], v[202:203] op_sel_hi:[1,0]
	v_pk_mul_f32 v[12:13], v[12:13], v[202:203] op_sel_hi:[1,0]
	v_pk_mul_f32 v[10:11], v[10:11], v[202:203] op_sel_hi:[1,0]
	v_pk_mul_f32 v[8:9], v[8:9], v[202:203] op_sel_hi:[1,0]
	v_pk_mul_f32 v[6:7], v[6:7], v[202:203] op_sel_hi:[1,0]
	v_pk_mul_f32 v[4:5], v[4:5], v[202:203] op_sel_hi:[1,0]
	v_pk_mul_f32 v[2:3], v[2:3], v[202:203] op_sel_hi:[1,0]
	v_pk_mul_f32 v[0:1], v[0:1], v[202:203] op_sel_hi:[1,0]
	v_pk_add_f32 v[64:65], v[64:65], v[184:185] op_sel_hi:[1,0] neg_lo:[0,1] neg_hi:[0,1]
	v_pk_add_f32 v[82:83], v[82:83], v[184:185] op_sel_hi:[1,0] neg_lo:[0,1] neg_hi:[0,1]
	v_pk_add_f32 v[66:67], v[66:67], v[184:185] op_sel_hi:[1,0] neg_lo:[0,1] neg_hi:[0,1]
	v_pk_add_f32 v[84:85], v[84:85], v[184:185] op_sel_hi:[1,0] neg_lo:[0,1] neg_hi:[0,1]
	v_pk_add_f32 v[68:69], v[68:69], v[184:185] op_sel_hi:[1,0] neg_lo:[0,1] neg_hi:[0,1]
	v_pk_add_f32 v[86:87], v[86:87], v[184:185] op_sel_hi:[1,0] neg_lo:[0,1] neg_hi:[0,1]
	v_pk_add_f32 v[70:71], v[70:71], v[184:185] op_sel_hi:[1,0] neg_lo:[0,1] neg_hi:[0,1]
	v_pk_add_f32 v[88:89], v[88:89], v[184:185] op_sel_hi:[1,0] neg_lo:[0,1] neg_hi:[0,1]
	v_pk_add_f32 v[72:73], v[72:73], v[184:185] op_sel_hi:[1,0] neg_lo:[0,1] neg_hi:[0,1]
	v_pk_add_f32 v[90:91], v[90:91], v[184:185] op_sel_hi:[1,0] neg_lo:[0,1] neg_hi:[0,1]
	v_pk_add_f32 v[74:75], v[74:75], v[184:185] op_sel_hi:[1,0] neg_lo:[0,1] neg_hi:[0,1]
	v_pk_add_f32 v[92:93], v[92:93], v[184:185] op_sel_hi:[1,0] neg_lo:[0,1] neg_hi:[0,1]
	v_pk_add_f32 v[76:77], v[76:77], v[184:185] op_sel_hi:[1,0] neg_lo:[0,1] neg_hi:[0,1]
	v_pk_add_f32 v[94:95], v[94:95], v[184:185] op_sel_hi:[1,0] neg_lo:[0,1] neg_hi:[0,1]
	v_pk_add_f32 v[78:79], v[78:79], v[184:185] op_sel_hi:[1,0] neg_lo:[0,1] neg_hi:[0,1]

; DI void softmax_pv(f32x16 (&sa)[2], f32x16 (&O)[4], float& m, float& l, const char* sV, int lr, int lh, bool first) {
;   float t0 = fmaxf(fmaxf(sa[0][0], sa[0][1]), sa[0][2]);
;   float t1 = fmaxf(fmaxf(sa[1][0], sa[1][1]), sa[1][2]);
; #pragma unroll
;   for (int i = 3; i < 15; i += 2) {
;     t0 = fmaxf(fmaxf(t0, sa[0][i]), sa[0][i + 1]);
;     t1 = fmaxf(fmaxf(t1, sa[1][i]), sa[1][i + 1]);
;   }
;   float tmax = fmaxf(fmaxf(t0, t1), fmaxf(sa[0][15], sa[1][15]));
;   tmax = fmaxf(tmax, __shfl_xor(tmax, 32, 64));
;   if (first || __any(tmax > SM_THR)) {
;     asm volatile("; rescale" ::: "memory");
;     const float delta = first ? tmax : fmaxf(tmax, 0.f);
;     const float alpha = __builtin_amdgcn_exp2f(-delta);
;     m += delta;
;     l *= alpha;
; #pragma unroll
;     for (int d = 0; d < 4; ++d)
; #pragma unroll
;       for (int i = 0; i < 16; ++i) O[d][i] *= alpha;
; #pragma unroll
;     for (int i = 0; i < 16; ++i) { sa[0][i] -= delta; sa[1][i] -= delta; }
;   }
.LBB0_231:
	s_nop 3
	v_max3_f32 v184, v80, v81, v82
	s_nop 0
	v_max3_f32 v202, v64, v65, v66
	v_max3_f32 v184, v184, v83, v84
	v_max3_f32 v202, v202, v67, v68
	v_max3_f32 v184, v184, v85, v86
	v_max3_f32 v202, v202, v69, v70
	v_max3_f32 v184, v184, v87, v88
	v_max3_f32 v202, v202, v71, v72
	v_max3_f32 v184, v184, v89, v90
	v_max3_f32 v202, v202, v73, v74
	v_max3_f32 v184, v184, v91, v92
	v_max3_f32 v202, v202, v75, v76
	v_max_f32_e32 v203, v79, v79
	v_max_f32_e32 v204, v95, v95
	v_max3_f32 v184, v184, v93, v94
	v_max3_f32 v202, v202, v77, v78
	v_max_f32_e32 v203, v204, v203
	v_max3_f32 v184, v184, v202, v203
	v_mov_b32_e32 v202, v184
	s_nop 1
	v_permlane32_swap_b32_e32 v202, v184
	s_nop 1
	v_max_f32_e32 v184, v184, v202
	v_cmp_lt_f32_e32 vcc, s87, v184
	s_cbranch_vccz .LBB0_233
	v_max_f32_e32 v184, v184, v184
	v_max_f32_e32 v184, 0, v184
	v_exp_f32_e64 v202, -v184
	v_add_f32_e32 v226, v226, v184
	v_pk_add_f32 v[80:81], v[80:81], v[184:185] op_sel_hi:[1,0] neg_lo:[0,1] neg_hi:[0,1]
	v_mul_f32_e32 v222, v222, v202
	v_pk_mul_f32 v[62:63], v[62:63], v[202:203] op_sel_hi:[1,0]
	v_pk_mul_f32 v[60:61], v[60:61], v[202:203] op_sel_hi:[1,0]
	v_pk_mul_f32 v[58:59], v[58:59], v[202:203] op_sel_hi:[1,0]
	v_pk_mul_f32 v[56:57], v[56:57], v[202:203] op_sel_hi:[1,0]
	v_pk_mul_f32 v[54:55], v[54:55], v[202:203] op_sel_hi:[1,0]
	v_pk_mul_f32 v[52:53], v[52:53], v[202:203] op_sel_hi:[1,0]
	v_pk_mul_f32 v[50:51], v[50:51], v[202:203] op_sel_hi:[1,0]
	v_pk_mul_f32 v[48:49], v[48:49], v[202:203] op_sel_hi:[1,0]
	v_pk_mul_f32 v[46:47], v[46:47], v[202:203] op_sel_hi:[1,0]
	v_pk_mul_f32 v[44:45], v[44:45], v[202:203] op_sel_hi:[1,0]
	v_pk_mul_f32 v[42:43], v[42:43], v[202:203] op_sel_hi:[1,0]
	v_pk_mul_f32 v[40:41], v[40:41], v[202:203] op_sel_hi:[1,0]
	v_pk_mul_f32 v[38:39], v[38:39], v[202:203] op_sel_hi:[1,0]
	v_pk_mul_f32 v[36:37], v[36:37], v[202:203] op_sel_hi:[1,0]
	v_pk_mul_f32 v[34:35], v[34:35], v[202:203] op_sel_hi:[1,0]
	v_pk_mul_f32 v[32:33], v[32:33], v[202:203] op_sel_hi:[1,0]
	v_pk_mul_f32 v[30:31], v[30:31], v[202:203] op_sel_hi:[1,0]
	v_pk_mul_f32 v[28:29], v[28:29], v[202:203] op_sel_hi:[1,0]
	v_pk_mul_f32 v[26:27], v[26:27], v[202:203] op_sel_hi:[1,0]
	v_pk_mul_f32 v[24:25], v[24:25], v[202:203] op_sel_hi:[1,0]
	v_pk_mul_f32 v[22:23], v[22:23], v[202:203] op_sel_hi:[1,0]
	v_pk_mul_f32 v[20:21], v[20:21], v[202:203] op_sel_hi:[1,0]
	v_pk_mul_f32 v[18:19], v[18:19], v[202:203] op_sel_hi:[1,0]
	v_pk_mul_f32 v[16:17], v[16:17], v[202:203] op_sel_hi:[1,0]
	v_pk_mul_f32 v[14:15], v[14:15], v[202:203] op_sel_hi:[1,0]
	v_pk_mul_f32 v[12:13], v[12:13], v[202:203] op_sel_hi:[1,0]
	v_pk_mul_f32 v[10:11], v[10:11], v[202:203] op_sel_hi:[1,0]
	v_pk_mul_f32 v[8:9], v[8:9], v[202:203] op_sel_hi:[1,0]
	v_pk_mul_f32 v[6:7], v[6:7], v[202:203] op_sel_hi:[1,0]
	v_pk_mul_f32 v[4:5], v[4:5], v[202:203] op_sel_hi:[1,0]
	v_pk_mul_f32 v[2:3], v[2:3], v[202:203] op_sel_hi:[1,0]
	v_pk_mul_f32 v[0:1], v[0:1], v[202:203] op_sel_hi:[1,0]
	v_pk_add_f32 v[64:65], v[64:65], v[184:185] op_sel_hi:[1,0] neg_lo:[0,1] neg_hi:[0,1]
	v_pk_add_f32 v[82:83], v[82:83], v[184:185] op_sel_hi:[1,0] neg_lo:[0,1] neg_hi:[0,1]
	v_pk_add_f32 v[66:67], v[66:67], v[184:185] op_sel_hi:[1,0] neg_lo:[0,1] neg_hi:[0,1]
	v_pk_add_f32 v[84:85], v[84:85], v[184:185] op_sel_hi:[1,0] neg_lo:[0,1] neg_hi:[0,1]
	v_pk_add_f32 v[68:69], v[68:69], v[184:185] op_sel_hi:[1,0] neg_lo:[0,1] neg_hi:[0,1]
	v_pk_add_f32 v[86:87], v[86:87], v[184:185] op_sel_hi:[1,0] neg_lo:[0,1] neg_hi:[0,1]
	v_pk_add_f32 v[70:71], v[70:71], v[184:185] op_sel_hi:[1,0] neg_lo:[0,1] neg_hi:[0,1]
	v_pk_add_f32 v[88:89], v[88:89], v[184:185] op_sel_hi:[1,0] neg_lo:[0,1] neg_hi:[0,1]
	v_pk_add_f32 v[72:73], v[72:73], v[184:185] op_sel_hi:[1,0] neg_lo:[0,1] neg_hi:[0,1]
	v_pk_add_f32 v[90:91], v[90:91], v[184:185] op_sel_hi:[1,0] neg_lo:[0,1] neg_hi:[0,1]
	v_pk_add_f32 v[74:75], v[74:75], v[184:185] op_sel_hi:[1,0] neg_lo:[0,1] neg_hi:[0,1]
	v_pk_add_f32 v[92:93], v[92:93], v[184:185] op_sel_hi:[1,0] neg_lo:[0,1] neg_hi:[0,1]
	v_pk_add_f32 v[76:77], v[76:77], v[184:185] op_sel_hi:[1,0] neg_lo:[0,1] neg_hi:[0,1]
	v_pk_add_f32 v[94:95], v[94:95], v[184:185] op_sel_hi:[1,0] neg_lo:[0,1] neg_hi:[0,1]
	v_pk_add_f32 v[78:79], v[78:79], v[184:185] op_sel_hi:[1,0] neg_lo:[0,1] neg_hi:[0,1]
